# phase 5: workgroups that run two sgu chunks (layer 0) skip prep_pool, the others share its rows
# baseline (speedup 1.0000x reference)
.LBB0_291:
	s_and_b64 vcc, exec, s[2:3]
	s_cbranch_vccz .LBB0_476
	v_readlane_b32 s2, v255, 12
	s_cmp_gt_i32 s2, 2
	s_mov_b64 s[2:3], -1
	s_cbranch_scc0 .LBB0_473
	v_readlane_b32 s2, v255, 12
	s_cmp_lt_i32 s2, 4
	s_mov_b64 s[2:3], -1
	s_cbranch_scc1 .LBB0_437
	v_readlane_b32 s2, v255, 12
	s_cmp_gt_i32 s2, 4
	s_mov_b64 s[2:3], -1
	s_cbranch_scc0 .LBB0_317
	v_readlane_b32 s37, v255, 9
	s_lshr_b32 s37, s37, 7
	s_sub_i32 s37, s37, s18
	s_max_i32 s37, s37, 0
	s_lshl_b32 s89, s37, 1
	s_cmp_gt_i32 s89, s18
	s_cselect_b32 s37, 0, s37
	s_sub_i32 s36, s20, s37
	s_sub_i32 s88, s18, s37
	s_lshl_b32 s36, s36, 3
	s_lshl_b32 s88, s88, 3
	s_cmp_lt_i32 s36, 0
	s_cselect_b32 s36, 0x7fffff00, s36
	v_ashrrev_i32_e32 v64, 6, v160
	v_add_u32_e32 v116, s36, v64
	v_cmp_gt_i32_e32 vcc, s77, v116
	v_ashrrev_i32_e32 v65, 31, v64
	s_and_saveexec_b64 s[62:63], vcc
	s_cbranch_execz .LBB0_308
	s_load_dwordx2 s[2:3], s[0:1], 0x70
	s_load_dwordx2 s[6:7], s[0:1], 0x60
	v_readlane_b32 s9, v255, 8
	s_lshl_b32 s24, s9, 7
	s_ashr_i32 s25, s24, 31
	s_lshl_b64 s[24:25], s[24:25], 2
	s_waitcnt lgkmcnt(0)
	s_add_u32 s2, s2, s24
	s_mul_i32 s24, s9, 0xc0
	s_addc_u32 s3, s3, s25
	s_ashr_i32 s25, s24, 31
	s_lshl_b64 s[24:25], s[24:25], 2
	s_add_u32 s6, s6, s24
	s_waitcnt vmcnt(0)
	v_and_b32_e32 v7, 63, v160
	v_bfe_u32 v0, v160, 4, 2
	s_addc_u32 s7, s7, s25
	v_lshlrev_b32_e64 v48, v0, 2
	v_lshlrev_b32_e32 v0, 2, v7
	global_load_dword v50, v0, s[6:7]
	global_load_dword v51, v0, s[6:7] offset:256
	global_load_dword v52, v0, s[6:7] offset:512
	global_load_dword v53, v0, s[2:3]
	global_load_dword v54, v0, s[2:3] offset:256
	v_and_b32_e32 v0, 64, v197
	v_add_u32_e32 v0, 64, v0
	v_xor_b32_e32 v1, 1, v197
	v_cmp_lt_i32_e32 vcc, v1, v0
	s_ashr_i32 s37, s36, 31
	v_lshl_add_u64 v[14:15], v[64:65], 0, s[36:37]
	v_cndmask_b32_e32 v1, v197, v1, vcc
	v_lshlrev_b32_e32 v55, 2, v1
	v_xor_b32_e32 v1, 2, v197
	v_cmp_lt_i32_e32 vcc, v1, v0
	v_lshlrev_b64 v[4:5], 11, v[14:15]
	s_mov_b64 s[2:3], 0x800600
	v_cndmask_b32_e32 v1, v197, v1, vcc
	v_lshlrev_b32_e32 v56, 2, v1
	v_xor_b32_e32 v1, 4, v197
	v_cmp_lt_i32_e32 vcc, v1, v0
	s_movk_i32 s6, 0x8c0
	v_lshlrev_b32_e32 v16, 1, v7
	v_cndmask_b32_e32 v1, v197, v1, vcc
	v_lshlrev_b32_e32 v57, 2, v1
	v_xor_b32_e32 v1, 8, v197
	v_cmp_lt_i32_e32 vcc, v1, v0
	v_mov_b32_e32 v17, v157
	v_and_b32_e32 v12, 31, v160
	v_cndmask_b32_e32 v1, v197, v1, vcc
	v_lshlrev_b32_e32 v58, 2, v1
	v_xor_b32_e32 v1, 16, v197
	v_cmp_lt_i32_e32 vcc, v1, v0
	v_cmp_gt_u32_e64 s[38:39], 16, v12
	v_mov_b32_e32 v6, 0
	v_cndmask_b32_e32 v1, v197, v1, vcc
	v_lshlrev_b32_e32 v59, 2, v1
	v_xor_b32_e32 v1, 32, v197
	v_cmp_lt_i32_e32 vcc, v1, v0
	s_ashr_i32 s89, s88, 31
	v_lshrrev_b32_e32 v49, 1, v48
	v_cndmask_b32_e32 v0, v197, v1, vcc
	v_and_b32_e32 v1, 7, v160
	v_cvt_f32_ubyte0_e32 v2, v1
	v_mul_f32_e32 v2, 0xbfd49a78, v2
	v_lshlrev_b32_e32 v60, 2, v0
	v_bfe_u32 v0, v160, 3, 1
	v_exp_f32_e32 v61, v2
	v_lshrrev_b32_e32 v2, 1, v160
	v_cmp_eq_u32_e64 s[40:41], 0, v0
	v_lshlrev_b32_e32 v0, 4, v0
	v_and_b32_e32 v2, 8, v2
	v_or3_b32 v0, v0, v2, v1
	v_lshlrev_b32_e32 v156, 1, v0
	v_lshl_add_u64 v[0:1], s[46:47], 0, v[156:157]
	v_lshlrev_b32_e32 v156, 3, v7
	v_or_b32_e32 v4, v4, v156
	v_lshl_add_u64 v[4:5], v[4:5], 0, s[2:3]
	v_mad_u64_u32 v[10:11], s[2:3], v14, s6, 0
	v_mad_u64_u32 v[8:9], s[2:3], v14, s6, v[16:17]
	v_mad_i32_i24 v9, v15, s6, v9
	s_mov_b64 s[2:3], 0x4c00100
	v_mad_i32_i24 v11, v15, s6, v11
	v_lshl_add_u64 v[8:9], v[8:9], 0, s[2:3]
	v_lshl_or_b32 v10, v12, 1, v10
	s_mov_b64 s[2:3], 0x4c00280
	v_lshl_add_u64 v[10:11], v[10:11], 0, s[2:3]
	v_mad_u64_u32 v[12:13], s[2:3], v14, s6, v[156:157]
	v_mad_i32_i24 v13, v15, s6, v13
	s_mov_b64 s[2:3], 0x4c006c0
	s_movk_i32 s6, 0x300
	v_lshl_add_u64 v[12:13], v[12:13], 0, s[2:3]
	v_mad_u64_u32 v[18:19], s[2:3], v14, s6, 0
	v_mad_i32_i24 v15, v15, s6, v19
	v_or_b32_e32 v14, v18, v16
	s_mov_b64 s[2:3], 0xb860180
	v_cmp_gt_u32_e64 s[42:43], 32, v7
	v_lshl_add_u64 v[2:3], s[30:31], 0, v[156:157]
	s_lshl_b64 s[66:67], s[88:89], 11
	s_mul_hi_i32 s69, s88, 0x8c0
	s_mul_i32 s68, s88, 0x8c0
	v_lshl_add_u64 v[14:15], v[14:15], 0, s[2:3]
	s_mul_hi_i32 s81, s88, 0x300
	s_mul_i32 s80, s88, 0x300
	s_mov_b64 s[84:85], 0
	v_mov_b32_e32 v62, v116
	v_mov_b32_e32 v7, v6
	v_mov_b32_e32 v16, v6
	v_mov_b32_e32 v17, v6
	v_mov_b32_e32 v18, v6
	v_mov_b32_e32 v19, v6
	v_mov_b32_e32 v20, v6
	v_mov_b32_e32 v21, v6
	v_mov_b32_e32 v22, v6
	v_mov_b32_e32 v23, v6
	v_mov_b32_e32 v24, v6
	v_mov_b32_e32 v25, v6
	v_mov_b32_e32 v26, v6
	v_mov_b32_e32 v27, v6
	v_mov_b32_e32 v28, v6
	v_mov_b32_e32 v29, v6
	v_mov_b32_e32 v30, v6
	v_mov_b32_e32 v31, v6
	v_mov_b32_e32 v32, v6
	v_mov_b32_e32 v33, v6
	v_mov_b32_e32 v34, v6
	v_mov_b32_e32 v35, v6
	v_mov_b32_e32 v36, v6
	v_mov_b32_e32 v37, v6
	v_mov_b32_e32 v38, v6
	v_mov_b32_e32 v39, v6
	v_mov_b32_e32 v40, v6
	v_mov_b32_e32 v41, v6
	v_mov_b32_e32 v42, v6
	v_mov_b32_e32 v43, v6
	v_mov_b32_e32 v44, v6
	v_mov_b32_e32 v45, v6
	s_branch .LBB0_298

.LBB0_308:
	s_or_b64 exec, exec, s[62:63]
	s_lshl_b32 s36, s20, 3
	s_lshl_b32 s88, s18, 3
	v_add_u32_e32 v116, s36, v64
	v_readlane_b32 s2, v255, 9
	s_lshr_b32 s2, s2, 7
	s_cmp_ge_i32 s20, s2
	s_cbranch_scc1 .LBB0_311
	s_load_dwordx2 s[6:7], s[0:1], 0x90
	s_load_dwordx2 s[24:25], s[0:1], 0x80
	v_readlane_b32 s3, v255, 8
	s_lshl_b32 s34, s3, 9
	s_ashr_i32 s35, s34, 31
	s_lshl_b64 s[34:35], s[34:35], 2
	s_waitcnt lgkmcnt(0)
	s_add_u32 s6, s6, s34
	s_addc_u32 s7, s7, s35
	s_lshl_b32 s34, s3, 8
	s_ashr_i32 s35, s34, 31
	s_lshl_b64 s[34:35], s[34:35], 2
	s_waitcnt vmcnt(0)
	v_ashrrev_i32_e32 v5, 1, v160
	s_add_u32 s24, s24, s34
	v_and_b32_e32 v0, 0xffffffc0, v5
	s_addc_u32 s25, s25, s35
	v_ashrrev_i32_e32 v1, 31, v0
	v_bfe_u32 v3, v160, 4, 2
	v_lshl_add_u64 v[66:67], v[0:1], 2, s[24:25]
	v_readlane_b32 s24, v255, 6
	v_and_b32_e32 v117, 0x7f, v160
	v_lshlrev_b32_e32 v6, 4, v3
	v_mov_b32_e32 v7, v157
	v_readlane_b32 s25, v255, 7
	v_lshl_add_u32 v2, v117, 1, 0
	v_and_b32_e32 v4, 0xffffffcf, v160
	v_lshl_add_u64 v[8:9], s[24:25], 0, v[6:7]
	s_mov_b64 s[24:25], 0x2740000
	s_movk_i32 s3, 0x110
	v_lshlrev_b32_e32 v156, 3, v3
	v_lshl_add_u64 v[8:9], v[8:9], 0, s[24:25]
	v_add_u32_e32 v13, 0, v6
	v_lshl_or_b32 v6, v3, 2, v0
	v_mad_u64_u32 v[68:69], s[24:25], v0, s3, v[2:3]
	v_or_b32_e32 v3, 63, v5
	v_ashrrev_i32_e32 v5, 31, v4
	v_lshlrev_b64 v[10:11], 8, v[4:5]
	v_lshl_add_u64 v[70:71], v[8:9], 0, v[10:11]
	v_or_b32_e32 v10, 16, v4
	v_ashrrev_i32_e32 v11, 31, v10
	v_lshlrev_b64 v[10:11], 8, v[10:11]
	v_lshl_add_u64 v[72:73], v[8:9], 0, v[10:11]
	v_or_b32_e32 v10, 32, v4
	v_ashrrev_i32_e32 v11, 31, v10
	v_lshlrev_b64 v[10:11], 8, v[10:11]
	v_lshl_add_u64 v[74:75], v[8:9], 0, v[10:11]
	v_or_b32_e32 v10, 48, v160
	v_ashrrev_i32_e32 v11, 31, v10
	v_and_b32_e32 v12, 0xffffff80, v160
	v_and_or_b32 v7, v160, 15, v0
	v_and_b32_e32 v118, 0x4f, v160
	v_lshlrev_b64 v[10:11], 8, v[10:11]
	v_mul_lo_u32 v3, v3, s3
	v_lshl_add_u64 v[76:77], v[8:9], 0, v[10:11]
	v_mul_lo_u32 v8, v7, s3
	v_lshl_add_u64 v[78:79], v[4:5], 2, s[6:7]
	v_ashrrev_i32_e32 v5, 31, v12
	v_or_b32_e32 v4, v12, v118
	v_ashrrev_i32_e32 v7, 31, v6
	v_lshl_add_u64 v[82:83], v[0:1], 1, s[30:31]
	v_lshl_add_u64 v[80:81], v[4:5], 2, s[6:7]
	v_lshl_add_u64 v[84:85], v[82:83], 0, v[156:157]
	v_lshl_add_u64 v[86:87], v[6:7], 1, s[58:59]
	s_lshl_b32 s3, s20, 7
	s_lshl_b32 s6, s18, 7
	v_add_u32_e32 v69, v2, v3
	v_add_u32_e32 v119, v13, v8
	s_mov_b32 s7, s20
	s_movk_i32 s9, 0x8c0
